# GLU epilogue: row-sum atomic issued after the next step's Y load, vmcnt(1) instead of vmcnt(0) so steps do not wait on the atomic round trip
# baseline (speedup 1.0000x reference)
; __device__ __forceinline__ u32x4 pack8(f32x4 v0, f32x4 v1) { u32x4 w; w.x = cvt_pk_bf16(v0[0], v0[1]); w.y = cvt_pk_bf16(v0[2], v0[3]); w.z = cvt_pk_bf16(v1[0], v1[1]); w.w = cvt_pk_bf16(v1[2], v1[3]); return w; }
; __device__ __forceinline__ float sigmoidf_(float x) { return __builtin_amdgcn_rcpf(1.f + __builtin_amdgcn_exp2f(-1.4426950408889634f * x)); }
;     __device__ __forceinline__ void operator()(EPI_ARGS) const {
; #pragma unroll
;         for (int bj = 0; bj < 2; ++bj) { const int col0 = EPI_COL(bj); const f32x4 b0 = *(const f32x4*)(bias + col0), b1 = *(const f32x4*)(bias + col0 + 4);
; #pragma unroll
;             for (int ai = 0; ai < 2; ++ai)
; #pragma unroll
;                 for (int m = 0; m < 4; ++m) { const int row = EPI_ROW(ai, m); const u32x4 yv = *(const u32x4*)(Y + (size_t)row * 1024 + col0);
;                     f32x4 v0 = acc[ai][bj][m][0] + b0, v1 = acc[ai][bj][m][1] + b1;
;                     v0[0] = __uint_as_float(yv.x << 16) * sigmoidf_(v0[0]); v0[1] = __uint_as_float(yv.x & 0xffff0000u) * sigmoidf_(v0[1]);
;                     v0[2] = __uint_as_float(yv.y << 16) * sigmoidf_(v0[2]); v0[3] = __uint_as_float(yv.y & 0xffff0000u) * sigmoidf_(v0[3]);
;                     v1[0] = __uint_as_float(yv.z << 16) * sigmoidf_(v1[0]); v1[1] = __uint_as_float(yv.z & 0xffff0000u) * sigmoidf_(v1[1]);
;                     v1[2] = __uint_as_float(yv.w << 16) * sigmoidf_(v1[2]); v1[3] = __uint_as_float(yv.w & 0xffff0000u) * sigmoidf_(v1[3]);
;                     *(u32x4*)(MIX + (size_t)row * 2048 + 1024 + col0) = pack8(v0, v1);
;                     float ss = (v0[0] * v0[0] + v0[1] * v0[1]) + (v0[2] * v0[2] + v0[3] * v0[3]) + (v1[0] * v1[0] + v1[1] * v1[1]) + (v1[2] * v1[2] + v1[3] * v1[3]);
;                     ss += __shfl_xor(ss, 16); ss += __shfl_xor(ss, 32);
;                     if (fq == 0) atomicAdd(rsq + row, ss); } }
;     }
.LBB0_599:
	v_lshl_or_b32 v142, s73, 8, v153
	v_lshl_add_u32 v146, s74, 8, v152
	v_readlane_b32 s68, v246, 25
	v_ashrrev_i32_e32 v143, 31, v142
	v_readlane_b32 s70, v246, 27
	v_readlane_b32 s71, v246, 28
	v_ashrrev_i32_e32 v147, 31, v146
	v_lshlrev_b64 v[144:145], 11, v[146:147]
	v_lshl_add_u64 v[140:141], v[142:143], 2, s[70:71]
	global_load_dwordx4 v[104:107], v[140:141], off offset:16
	global_load_dwordx4 v[108:111], v[140:141], off
	v_lshl_add_u64 v[166:167], s[88:89], 0, v[144:145]
	v_lshlrev_b64 v[144:145], 1, v[142:143]
	v_lshl_add_u64 v[142:143], v[166:167], 0, v[144:145]
	global_load_dwordx4 v[170:173], v[142:143], off
	v_readlane_b32 s69, v246, 26
	v_readlane_b32 s72, v246, 29
	v_readlane_b32 s73, v246, 30
	v_readlane_b32 s74, v246, 31
	v_readlane_b32 s75, v246, 32
	v_readlane_b32 s76, v246, 33
	v_readlane_b32 s77, v246, 34
	v_readlane_b32 s78, v246, 35
	v_readlane_b32 s79, v246, 36
	v_readlane_b32 s80, v246, 37
	v_readlane_b32 s81, v246, 38
	v_readlane_b32 s82, v246, 39
	v_readlane_b32 s83, v246, 40
	s_waitcnt vmcnt(2)
	v_pk_add_f32 v[128:129], v[128:129], v[104:105]
	s_waitcnt vmcnt(1)
	v_pk_add_f32 v[132:133], v[132:133], v[108:109]
	v_pk_add_f32 v[134:135], v[134:135], v[110:111]
	v_mul_f32_e32 v132, 0xbfb8aa3b, v132
	v_exp_f32_e32 v132, v132
	v_mul_f32_e32 v133, 0xbfb8aa3b, v133
	v_exp_f32_e32 v133, v133
	s_waitcnt vmcnt(0)
	v_lshlrev_b32_e32 v163, 16, v170
	v_add_f32_e32 v132, 1.0, v132
	v_rcp_f32_e32 v132, v132
	v_add_f32_e32 v133, 1.0, v133
	v_rcp_f32_e32 v133, v133
	v_mul_f32_e32 v128, 0xbfb8aa3b, v128
	v_mul_f32_e32 v163, v132, v163
	v_and_b32_e32 v132, 0xffff0000, v170
	v_mul_f32_e32 v165, v133, v132
	v_mul_f32_e32 v133, 0xbfb8aa3b, v134
	v_exp_f32_e32 v133, v133
	v_lshlrev_b32_e32 v132, 16, v171
	v_exp_f32_e32 v128, v128
	v_mul_f32_e32 v129, 0xbfb8aa3b, v129
	v_add_f32_e32 v133, 1.0, v133
	v_rcp_f32_e32 v133, v133
	v_exp_f32_e32 v129, v129
	v_add_f32_e32 v128, 1.0, v128
	v_rcp_f32_e32 v128, v128
	v_mul_f32_e32 v134, v133, v132
	v_mul_f32_e32 v133, 0xbfb8aa3b, v135
	v_exp_f32_e32 v133, v133
	v_add_f32_e32 v129, 1.0, v129
	v_rcp_f32_e32 v129, v129
	v_and_b32_e32 v132, 0xffff0000, v171
	v_add_f32_e32 v133, 1.0, v133
	v_rcp_f32_e32 v133, v133
	v_pk_add_f32 v[130:131], v[130:131], v[106:107]
	v_mul_f32_e32 v135, v133, v132
	v_lshlrev_b32_e32 v132, 16, v172
	v_mul_f32_e32 v166, v128, v132
	v_and_b32_e32 v128, 0xffff0000, v172
	v_mul_f32_e32 v167, v129, v128
	v_mul_f32_e32 v129, 0xbfb8aa3b, v130
	v_exp_f32_e32 v129, v129
	v_lshlrev_b32_e32 v128, 16, v173
	v_cvt_pk_bf16_f32 v130, v163, v165
	v_add_f32_e32 v129, 1.0, v129
	v_rcp_f32_e32 v129, v129
	s_nop 0
	v_mul_f32_e32 v170, v129, v128
	v_mul_f32_e32 v129, 0xbfb8aa3b, v131
	v_exp_f32_e32 v129, v129
	v_and_b32_e32 v128, 0xffff0000, v173
	v_cvt_pk_bf16_f32 v131, v134, v135
	v_cvt_pk_bf16_f32 v132, v166, v167
	v_add_f32_e32 v129, 1.0, v129
	v_rcp_f32_e32 v129, v129
	s_nop 0
	v_mul_f32_e32 v171, v129, v128
	v_lshlrev_b64 v[128:129], 12, v[146:147]
	v_lshl_add_u64 v[128:129], s[58:59], 0, v[128:129]
	v_lshl_add_u64 v[128:129], v[128:129], 0, v[144:145]
	v_cvt_pk_bf16_f32 v133, v170, v171
	global_store_dwordx4 v[128:129], v[130:133], off offset:2048
	s_nop 1
	v_mul_f32_e32 v130, v165, v165
	v_mul_f32_e32 v131, v135, v135
	v_fmac_f32_e32 v130, v163, v163
	v_fmac_f32_e32 v131, v134, v134
	v_add_f32_e32 v130, v130, v131
	v_mul_f32_e32 v131, v167, v167
	v_fmac_f32_e32 v131, v166, v166
	v_add_f32_e32 v130, v130, v131
	v_mul_f32_e32 v131, v171, v171
	v_fmac_f32_e32 v131, v170, v170
	v_and_b32_e32 v132, 64, v161
	v_add_f32_e32 v130, v131, v130
	v_xor_b32_e32 v131, 16, v161
	v_add_u32_e32 v133, 64, v132
	v_cmp_lt_i32_e32 vcc, v131, v133
	s_nop 1
	v_cndmask_b32_e32 v131, v161, v131, vcc
	v_lshlrev_b32_e32 v134, 2, v131
	ds_bpermute_b32 v131, v134, v130
	s_waitcnt lgkmcnt(0)
	v_add_f32_e32 v132, v130, v131
	v_xor_b32_e32 v130, 32, v161
	v_cmp_lt_i32_e32 vcc, v130, v133
	s_nop 1
	v_cndmask_b32_e32 v130, v161, v130, vcc
	v_lshlrev_b32_e32 v135, 2, v130
	ds_bpermute_b32 v133, v135, v132
	v_lshl_add_u64 v[130:131], v[146:147], 2, s[64:65]
	s_waitcnt lgkmcnt(0)
	v_add_f32_e32 v176, v132, v133
	v_mov_b32_e32 v178, v130
	v_mov_b32_e32 v179, v131
	v_or_b32_e32 v166, 16, v146
	v_ashrrev_i32_e32 v167, 31, v166
	s_waitcnt lgkmcnt(0)
	v_lshlrev_b64 v[132:133], 11, v[166:167]
	v_lshl_add_u64 v[132:133], s[88:89], 0, v[132:133]
	v_lshl_add_u64 v[132:133], v[132:133], 0, v[144:145]
	global_load_dwordx4 v[170:173], v[132:133], off
	s_and_saveexec_b64 s[10:11], s[4:5]
	global_atomic_add_f32 v[178:179], v176, off
	s_mov_b64 exec, s[10:11]
	v_pk_add_f32 v[126:127], v[126:127], v[110:111]
	v_pk_add_f32 v[124:125], v[124:125], v[108:109]
	v_pk_add_f32 v[120:121], v[120:121], v[104:105]
	v_mul_f32_e32 v125, 0xbfb8aa3b, v125
	v_mul_f32_e32 v127, 0xbfb8aa3b, v127
	v_pk_add_f32 v[122:123], v[122:123], v[106:107]
	v_mul_f32_e32 v124, 0xbfb8aa3b, v124
	v_mul_f32_e32 v126, 0xbfb8aa3b, v126
	v_mul_f32_e32 v121, 0xbfb8aa3b, v121
	v_exp_f32_e32 v125, v125
	v_exp_f32_e32 v127, v127
	v_mul_f32_e32 v120, 0xbfb8aa3b, v120
	v_mul_f32_e32 v123, 0xbfb8aa3b, v123
	v_exp_f32_e32 v124, v124
	v_exp_f32_e32 v126, v126
	v_exp_f32_e32 v121, v121
	v_mul_f32_e32 v122, 0xbfb8aa3b, v122
	v_exp_f32_e32 v120, v120
	v_exp_f32_e32 v123, v123
	v_exp_f32_e32 v122, v122
	v_add_f32_e32 v125, 1.0, v125
	v_add_f32_e32 v127, 1.0, v127
	v_add_f32_e32 v124, 1.0, v124
	v_add_f32_e32 v126, 1.0, v126
	v_add_f32_e32 v121, 1.0, v121
	v_rcp_f32_e32 v125, v125
	v_rcp_f32_e32 v127, v127
	v_add_f32_e32 v120, 1.0, v120
	v_add_f32_e32 v123, 1.0, v123
	v_rcp_f32_e32 v124, v124
	v_rcp_f32_e32 v126, v126
	v_rcp_f32_e32 v121, v121
	v_add_f32_e32 v122, 1.0, v122
	v_rcp_f32_e32 v120, v120
	v_rcp_f32_e32 v123, v123
	v_rcp_f32_e32 v122, v122
	s_waitcnt vmcnt(1)
; __device__ __forceinline__ u32x4 pack8(f32x4 v0, f32x4 v1) { u32x4 w; w.x = cvt_pk_bf16(v0[0], v0[1]); w.y = cvt_pk_bf16(v0[2], v0[3]); w.z = cvt_pk_bf16(v1[0], v1[1]); w.w = cvt_pk_bf16(v1[2], v1[3]); return w; }
; __device__ __forceinline__ float sigmoidf_(float x) { return __builtin_amdgcn_rcpf(1.f + __builtin_amdgcn_exp2f(-1.4426950408889634f * x)); }
;     __device__ __forceinline__ void operator()(EPI_ARGS) const {
;     ...
;                 for (int m = 0; m < 4; ++m) { const int row = EPI_ROW(ai, m); const u32x4 yv = *(const u32x4*)(Y + (size_t)row * 1024 + col0);
;                     f32x4 v0 = acc[ai][bj][m][0] + b0, v1 = acc[ai][bj][m][1] + b1;
;                     v0[0] = __uint_as_float(yv.x << 16) * sigmoidf_(v0[0]); v0[1] = __uint_as_float(yv.x & 0xffff0000u) * sigmoidf_(v0[1]);
;                     v0[2] = __uint_as_float(yv.y << 16) * sigmoidf_(v0[2]); v0[3] = __uint_as_float(yv.y & 0xffff0000u) * sigmoidf_(v0[3]);
;                     v1[0] = __uint_as_float(yv.z << 16) * sigmoidf_(v1[0]); v1[1] = __uint_as_float(yv.z & 0xffff0000u) * sigmoidf_(v1[1]);
;                     v1[2] = __uint_as_float(yv.w << 16) * sigmoidf_(v1[2]); v1[3] = __uint_as_float(yv.w & 0xffff0000u) * sigmoidf_(v1[3]);
;                     *(u32x4*)(MIX + (size_t)row * 2048 + 1024 + col0) = pack8(v0, v1);
;                     float ss = (v0[0] * v0[0] + v0[1] * v0[1]) + (v0[2] * v0[2] + v0[3] * v0[3]) + (v1[0] * v1[0] + v1[1] * v1[1]) + (v1[2] * v1[2] + v1[3] * v1[3]);
;                     ss += __shfl_xor(ss, 16); ss += __shfl_xor(ss, 32);
;                     if (fq == 0) atomicAdd(rsq + row, ss); } }
	v_lshlrev_b32_e32 v147, 16, v170
	v_and_b32_e32 v163, 0xffff0000, v170
	v_and_b32_e32 v170, 0xffff0000, v171
	v_lshlrev_b32_e32 v165, 16, v171
	v_lshlrev_b32_e32 v171, 16, v172
	v_and_b32_e32 v172, 0xffff0000, v172
	v_mul_f32_e32 v125, v125, v163
	v_mul_f32_e32 v127, v127, v170
	v_lshlrev_b32_e32 v174, 16, v173
	v_and_b32_e32 v173, 0xffff0000, v173
	v_mul_f32_e32 v124, v124, v147
	v_mul_f32_e32 v126, v126, v165
	v_mul_f32_e32 v121, v121, v172
	v_cvt_pk_bf16_f32 v170, v124, v125
	v_mul_f32_e32 v125, v125, v125
	v_mul_f32_e32 v147, v127, v127
	v_mul_f32_e32 v120, v120, v171
	v_mul_f32_e32 v123, v123, v173
	v_mul_f32_e32 v163, v121, v121
	v_fmac_f32_e32 v125, v124, v124
	v_fmac_f32_e32 v147, v126, v126
	v_mul_f32_e32 v122, v122, v174
	v_mul_f32_e32 v165, v123, v123
	v_fmac_f32_e32 v163, v120, v120
	v_add_f32_e32 v124, v125, v147
	v_add_f32_e32 v124, v163, v124
	v_fmac_f32_e32 v165, v122, v122
	v_add_f32_e32 v124, v165, v124
	ds_bpermute_b32 v125, v134, v124
	v_cvt_pk_bf16_f32 v171, v126, v127
	v_cvt_pk_bf16_f32 v172, v120, v121
	v_lshlrev_b64 v[120:121], 12, v[166:167]
	v_lshl_add_u64 v[120:121], s[58:59], 0, v[120:121]
	s_waitcnt lgkmcnt(0)
	v_add_f32_e32 v124, v124, v125
	ds_bpermute_b32 v125, v135, v124
	v_cvt_pk_bf16_f32 v173, v122, v123
	v_lshl_add_u64 v[122:123], v[120:121], 0, v[144:145]
	v_lshl_add_u64 v[120:121], v[166:167], 2, s[64:65]
	global_store_dwordx4 v[122:123], v[170:173], off offset:2048
	s_waitcnt lgkmcnt(0)
	v_add_f32_e32 v176, v124, v125
	v_mov_b32_e32 v178, v120
	v_mov_b32_e32 v179, v121
	v_or_b32_e32 v126, 32, v146
	v_ashrrev_i32_e32 v127, 31, v126
	s_waitcnt lgkmcnt(0)
	v_lshlrev_b64 v[124:125], 11, v[126:127]
	v_lshl_add_u64 v[124:125], s[88:89], 0, v[124:125]
	v_lshl_add_u64 v[124:125], v[124:125], 0, v[144:145]
	global_load_dwordx4 v[170:173], v[124:125], off
	s_and_saveexec_b64 s[10:11], s[4:5]
	global_atomic_add_f32 v[178:179], v176, off
	s_mov_b64 exec, s[10:11]
	v_pk_add_f32 v[118:119], v[118:119], v[110:111]
	v_pk_add_f32 v[116:117], v[116:117], v[108:109]
	v_pk_add_f32 v[112:113], v[112:113], v[104:105]
	v_mul_f32_e32 v117, 0xbfb8aa3b, v117
	v_mul_f32_e32 v119, 0xbfb8aa3b, v119
	v_pk_add_f32 v[114:115], v[114:115], v[106:107]
	v_mul_f32_e32 v116, 0xbfb8aa3b, v116
	v_mul_f32_e32 v118, 0xbfb8aa3b, v118
	v_mul_f32_e32 v113, 0xbfb8aa3b, v113
	v_exp_f32_e32 v117, v117
	v_exp_f32_e32 v119, v119
	v_mul_f32_e32 v112, 0xbfb8aa3b, v112
	v_mul_f32_e32 v115, 0xbfb8aa3b, v115
	v_exp_f32_e32 v116, v116
	v_exp_f32_e32 v118, v118
	v_exp_f32_e32 v113, v113
	v_mul_f32_e32 v114, 0xbfb8aa3b, v114
	v_exp_f32_e32 v112, v112
	v_exp_f32_e32 v115, v115
	v_exp_f32_e32 v114, v114
	v_add_f32_e32 v117, 1.0, v117
	v_add_f32_e32 v119, 1.0, v119
	v_add_f32_e32 v116, 1.0, v116
	v_add_f32_e32 v118, 1.0, v118
	v_add_f32_e32 v113, 1.0, v113
	v_rcp_f32_e32 v117, v117
	v_rcp_f32_e32 v119, v119
	v_add_f32_e32 v112, 1.0, v112
	v_add_f32_e32 v115, 1.0, v115
	v_rcp_f32_e32 v116, v116
	v_rcp_f32_e32 v118, v118
	v_rcp_f32_e32 v113, v113
	v_add_f32_e32 v114, 1.0, v114
	v_rcp_f32_e32 v112, v112
	v_rcp_f32_e32 v115, v115
	v_rcp_f32_e32 v114, v114
	s_waitcnt vmcnt(1)
	v_and_b32_e32 v163, 0xffff0000, v170
	v_and_b32_e32 v166, 0xffff0000, v171
	v_lshlrev_b32_e32 v147, 16, v170
	v_lshlrev_b32_e32 v165, 16, v171
	v_and_b32_e32 v170, 0xffff0000, v172
	v_mul_f32_e32 v117, v117, v163
	v_mul_f32_e32 v119, v119, v166
	v_lshlrev_b32_e32 v167, 16, v172
	v_and_b32_e32 v172, 0xffff0000, v173
	v_mul_f32_e32 v116, v116, v147
	v_mul_f32_e32 v118, v118, v165
	v_mul_f32_e32 v113, v113, v170
	v_cvt_pk_bf16_f32 v170, v116, v117
	v_mul_f32_e32 v117, v117, v117
	v_mul_f32_e32 v147, v119, v119
	v_lshlrev_b32_e32 v171, 16, v173
	v_mul_f32_e32 v112, v112, v167
	v_mul_f32_e32 v115, v115, v172
	v_mul_f32_e32 v163, v113, v113
	v_fmac_f32_e32 v117, v116, v116
	v_fmac_f32_e32 v147, v118, v118
	v_mul_f32_e32 v114, v114, v171
	v_mul_f32_e32 v165, v115, v115
	v_fmac_f32_e32 v163, v112, v112
	v_add_f32_e32 v116, v117, v147
	v_add_f32_e32 v116, v163, v116
	v_fmac_f32_e32 v165, v114, v114
	v_add_f32_e32 v116, v165, v116
	ds_bpermute_b32 v117, v134, v116
	v_cvt_pk_bf16_f32 v171, v118, v119
	v_cvt_pk_bf16_f32 v172, v112, v113
	v_lshlrev_b64 v[112:113], 12, v[126:127]
	v_lshl_add_u64 v[112:113], s[58:59], 0, v[112:113]
	s_waitcnt lgkmcnt(0)
	v_add_f32_e32 v116, v116, v117
	ds_bpermute_b32 v117, v135, v116
	v_cvt_pk_bf16_f32 v173, v114, v115
	v_lshl_add_u64 v[114:115], v[112:113], 0, v[144:145]
	v_lshl_add_u64 v[112:113], v[126:127], 2, s[64:65]
	global_store_dwordx4 v[114:115], v[170:173], off offset:2048
	s_mov_b64 s[76:77], s[92:93]
	s_mov_b64 s[78:79], s[94:95]
	s_waitcnt lgkmcnt(0)
	v_add_f32_e32 v176, v116, v117
	v_mov_b32_e32 v178, v112
	v_mov_b32_e32 v179, v113
	v_or_b32_e32 v118, 48, v146
	v_ashrrev_i32_e32 v119, 31, v118
	s_waitcnt lgkmcnt(0)
	v_lshlrev_b64 v[116:117], 11, v[118:119]
	v_lshl_add_u64 v[116:117], s[88:89], 0, v[116:117]
	v_lshl_add_u64 v[116:117], v[116:117], 0, v[144:145]
	global_load_dwordx4 v[170:173], v[116:117], off
	s_and_saveexec_b64 s[10:11], s[4:5]
	global_atomic_add_f32 v[178:179], v176, off
	s_mov_b64 exec, s[10:11]
	v_pk_add_f32 v[102:103], v[102:103], v[110:111]
	v_pk_add_f32 v[100:101], v[100:101], v[108:109]
	v_pk_add_f32 v[98:99], v[98:99], v[106:107]
	v_pk_add_f32 v[96:97], v[96:97], v[104:105]
	v_mul_f32_e32 v101, 0xbfb8aa3b, v101
	v_mul_f32_e32 v103, 0xbfb8aa3b, v103
	v_mul_f32_e32 v100, 0xbfb8aa3b, v100
	v_mul_f32_e32 v102, 0xbfb8aa3b, v102
	v_mul_f32_e32 v97, 0xbfb8aa3b, v97
	v_mul_f32_e32 v99, 0xbfb8aa3b, v99
	v_exp_f32_e32 v101, v101
	v_exp_f32_e32 v103, v103
	v_mul_f32_e32 v96, 0xbfb8aa3b, v96
	v_exp_f32_e32 v100, v100
	v_exp_f32_e32 v102, v102
	v_exp_f32_e32 v97, v97
	v_exp_f32_e32 v99, v99
	v_mul_f32_e32 v98, 0xbfb8aa3b, v98
	v_exp_f32_e32 v96, v96
	v_exp_f32_e32 v98, v98
	v_add_f32_e32 v101, 1.0, v101
	v_add_f32_e32 v103, 1.0, v103
	v_add_f32_e32 v100, 1.0, v100
	v_add_f32_e32 v102, 1.0, v102
	v_add_f32_e32 v97, 1.0, v97
	v_add_f32_e32 v99, 1.0, v99
	v_rcp_f32_e32 v101, v101
	v_rcp_f32_e32 v103, v103
	v_add_f32_e32 v96, 1.0, v96
	v_rcp_f32_e32 v100, v100
	v_rcp_f32_e32 v102, v102
	v_rcp_f32_e32 v97, v97
	v_rcp_f32_e32 v99, v99
	v_add_f32_e32 v98, 1.0, v98
	v_rcp_f32_e32 v96, v96
	v_rcp_f32_e32 v98, v98
	s_waitcnt vmcnt(1)
; __device__ __forceinline__ u32x4 pack8(f32x4 v0, f32x4 v1) { u32x4 w; w.x = cvt_pk_bf16(v0[0], v0[1]); w.y = cvt_pk_bf16(v0[2], v0[3]); w.z = cvt_pk_bf16(v1[0], v1[1]); w.w = cvt_pk_bf16(v1[2], v1[3]); return w; }
; __device__ __forceinline__ float sigmoidf_(float x) { return __builtin_amdgcn_rcpf(1.f + __builtin_amdgcn_exp2f(-1.4426950408889634f * x)); }
;     __device__ __forceinline__ void operator()(EPI_ARGS) const {
;     ...
;                 for (int m = 0; m < 4; ++m) { const int row = EPI_ROW(ai, m); const u32x4 yv = *(const u32x4*)(Y + (size_t)row * 1024 + col0);
;                     f32x4 v0 = acc[ai][bj][m][0] + b0, v1 = acc[ai][bj][m][1] + b1;
;                     v0[0] = __uint_as_float(yv.x << 16) * sigmoidf_(v0[0]); v0[1] = __uint_as_float(yv.x & 0xffff0000u) * sigmoidf_(v0[1]);
;                     v0[2] = __uint_as_float(yv.y << 16) * sigmoidf_(v0[2]); v0[3] = __uint_as_float(yv.y & 0xffff0000u) * sigmoidf_(v0[3]);
;                     v1[0] = __uint_as_float(yv.z << 16) * sigmoidf_(v1[0]); v1[1] = __uint_as_float(yv.z & 0xffff0000u) * sigmoidf_(v1[1]);
;                     v1[2] = __uint_as_float(yv.w << 16) * sigmoidf_(v1[2]); v1[3] = __uint_as_float(yv.w & 0xffff0000u) * sigmoidf_(v1[3]);
;                     *(u32x4*)(MIX + (size_t)row * 2048 + 1024 + col0) = pack8(v0, v1);
;                     float ss = (v0[0] * v0[0] + v0[1] * v0[1]) + (v0[2] * v0[2] + v0[3] * v0[3]) + (v1[0] * v1[0] + v1[1] * v1[1]) + (v1[2] * v1[2] + v1[3] * v1[3]);
;                     ss += __shfl_xor(ss, 16); ss += __shfl_xor(ss, 32);
;                     if (fq == 0) atomicAdd(rsq + row, ss); } }
	v_and_b32_e32 v127, 0xffff0000, v170
	v_and_b32_e32 v163, 0xffff0000, v171
	v_lshlrev_b32_e32 v126, 16, v170
	v_lshlrev_b32_e32 v147, 16, v171
	v_and_b32_e32 v166, 0xffff0000, v172
	v_and_b32_e32 v170, 0xffff0000, v173
	v_mul_f32_e32 v101, v101, v127
	v_mul_f32_e32 v103, v103, v163
	v_lshlrev_b32_e32 v165, 16, v172
	v_mul_f32_e32 v100, v100, v126
	v_mul_f32_e32 v102, v102, v147
	v_mul_f32_e32 v97, v97, v166
	v_mul_f32_e32 v99, v99, v170
	v_cvt_pk_bf16_f32 v170, v100, v101
	v_mul_f32_e32 v101, v101, v101
	v_mul_f32_e32 v126, v103, v103
	v_lshlrev_b32_e32 v167, 16, v173
	v_mul_f32_e32 v96, v96, v165
	v_mul_f32_e32 v127, v97, v97
	v_fmac_f32_e32 v101, v100, v100
	v_fmac_f32_e32 v126, v102, v102
	v_mul_f32_e32 v98, v98, v167
	v_mul_f32_e32 v147, v99, v99
	v_fmac_f32_e32 v127, v96, v96
	v_add_f32_e32 v100, v101, v126
	v_add_f32_e32 v100, v127, v100
	v_fmac_f32_e32 v147, v98, v98
	v_add_f32_e32 v100, v147, v100
	ds_bpermute_b32 v101, v134, v100
	v_cvt_pk_bf16_f32 v171, v102, v103
	v_cvt_pk_bf16_f32 v172, v96, v97
	v_lshlrev_b64 v[96:97], 12, v[118:119]
	v_lshl_add_u64 v[96:97], s[58:59], 0, v[96:97]
	s_waitcnt lgkmcnt(0)
	v_add_f32_e32 v100, v100, v101
	ds_bpermute_b32 v101, v135, v100
	v_cvt_pk_bf16_f32 v173, v98, v99
	v_lshl_add_u64 v[98:99], v[96:97], 0, v[144:145]
	v_lshl_add_u64 v[96:97], v[118:119], 2, s[64:65]
	global_store_dwordx4 v[98:99], v[170:173], off offset:2048
	s_waitcnt lgkmcnt(0)
	v_add_f32_e32 v176, v100, v101
	v_mov_b32_e32 v178, v96
	v_mov_b32_e32 v179, v97
	v_add_u32_e32 v102, 0x80, v146
	v_ashrrev_i32_e32 v103, 31, v102
	s_waitcnt lgkmcnt(0)
	v_lshlrev_b64 v[100:101], 11, v[102:103]
	v_lshl_add_u64 v[100:101], s[88:89], 0, v[100:101]
	v_lshl_add_u64 v[100:101], v[100:101], 0, v[144:145]
	global_load_dwordx4 v[170:173], v[100:101], off
	s_and_saveexec_b64 s[10:11], s[4:5]
	global_atomic_add_f32 v[178:179], v176, off
	s_mov_b64 exec, s[10:11]
	v_pk_add_f32 v[94:95], v[94:95], v[110:111]
	v_pk_add_f32 v[92:93], v[92:93], v[108:109]
	v_pk_add_f32 v[88:89], v[88:89], v[104:105]
	v_mul_f32_e32 v93, 0xbfb8aa3b, v93
	v_mul_f32_e32 v95, 0xbfb8aa3b, v95
	v_pk_add_f32 v[90:91], v[90:91], v[106:107]
	v_mul_f32_e32 v92, 0xbfb8aa3b, v92
	v_mul_f32_e32 v94, 0xbfb8aa3b, v94
	v_mul_f32_e32 v89, 0xbfb8aa3b, v89
	v_exp_f32_e32 v93, v93
	v_exp_f32_e32 v95, v95
	v_mul_f32_e32 v88, 0xbfb8aa3b, v88
	v_mul_f32_e32 v91, 0xbfb8aa3b, v91
	v_exp_f32_e32 v92, v92
	v_exp_f32_e32 v94, v94
	v_exp_f32_e32 v89, v89
	v_mul_f32_e32 v90, 0xbfb8aa3b, v90
	v_exp_f32_e32 v88, v88
	v_exp_f32_e32 v91, v91
	v_exp_f32_e32 v90, v90
	v_add_f32_e32 v93, 1.0, v93
	v_add_f32_e32 v95, 1.0, v95
	v_add_f32_e32 v92, 1.0, v92
	v_add_f32_e32 v94, 1.0, v94
	v_add_f32_e32 v89, 1.0, v89
	v_rcp_f32_e32 v93, v93
	v_rcp_f32_e32 v95, v95
	v_add_f32_e32 v88, 1.0, v88
	v_add_f32_e32 v91, 1.0, v91
	v_rcp_f32_e32 v92, v92
	v_rcp_f32_e32 v94, v94
	v_rcp_f32_e32 v89, v89
	v_add_f32_e32 v90, 1.0, v90
	v_rcp_f32_e32 v88, v88
	v_rcp_f32_e32 v91, v91
	v_rcp_f32_e32 v90, v90
	s_waitcnt vmcnt(1)
	v_and_b32_e32 v119, 0xffff0000, v170
	v_and_b32_e32 v127, 0xffff0000, v171
	v_lshlrev_b32_e32 v118, 16, v170
	v_lshlrev_b32_e32 v126, 16, v171
	v_and_b32_e32 v163, 0xffff0000, v172
	v_mul_f32_e32 v93, v93, v119
	v_mul_f32_e32 v95, v95, v127
	v_lshlrev_b32_e32 v147, 16, v172
	v_and_b32_e32 v166, 0xffff0000, v173
	v_mul_f32_e32 v92, v92, v118
	v_mul_f32_e32 v94, v94, v126
	v_mul_f32_e32 v89, v89, v163
	v_cvt_pk_bf16_f32 v170, v92, v93
	v_mul_f32_e32 v93, v93, v93
	v_mul_f32_e32 v118, v95, v95
	v_lshlrev_b32_e32 v165, 16, v173
	v_mul_f32_e32 v88, v88, v147
	v_mul_f32_e32 v91, v91, v166
	v_mul_f32_e32 v119, v89, v89
	v_fmac_f32_e32 v93, v92, v92
	v_fmac_f32_e32 v118, v94, v94
	v_mul_f32_e32 v90, v90, v165
	v_mul_f32_e32 v126, v91, v91
	v_fmac_f32_e32 v119, v88, v88
	v_add_f32_e32 v92, v93, v118
	v_add_f32_e32 v92, v119, v92
	v_fmac_f32_e32 v126, v90, v90
	v_add_f32_e32 v92, v126, v92
	ds_bpermute_b32 v93, v134, v92
	v_cvt_pk_bf16_f32 v171, v94, v95
	v_cvt_pk_bf16_f32 v172, v88, v89
	v_lshlrev_b64 v[88:89], 12, v[102:103]
	v_lshl_add_u64 v[88:89], s[58:59], 0, v[88:89]
	s_waitcnt lgkmcnt(0)
	v_add_f32_e32 v92, v92, v93
	ds_bpermute_b32 v93, v135, v92
	v_cvt_pk_bf16_f32 v173, v90, v91
	v_lshl_add_u64 v[90:91], v[88:89], 0, v[144:145]
	v_lshl_add_u64 v[88:89], v[102:103], 2, s[64:65]
	global_store_dwordx4 v[90:91], v[170:173], off offset:2048
	s_waitcnt lgkmcnt(0)
	v_add_f32_e32 v176, v92, v93
	v_mov_b32_e32 v178, v88
	v_mov_b32_e32 v179, v89
	v_add_u32_e32 v94, 0x90, v146
	v_ashrrev_i32_e32 v95, 31, v94
	s_waitcnt lgkmcnt(0)
	v_lshlrev_b64 v[92:93], 11, v[94:95]
	v_lshl_add_u64 v[92:93], s[88:89], 0, v[92:93]
	v_lshl_add_u64 v[92:93], v[92:93], 0, v[144:145]
	global_load_dwordx4 v[170:173], v[92:93], off
	s_and_saveexec_b64 s[10:11], s[4:5]
	global_atomic_add_f32 v[178:179], v176, off
	s_mov_b64 exec, s[10:11]
	v_pk_add_f32 v[86:87], v[86:87], v[110:111]
	v_pk_add_f32 v[84:85], v[84:85], v[108:109]
	v_pk_add_f32 v[80:81], v[80:81], v[104:105]
	v_mul_f32_e32 v85, 0xbfb8aa3b, v85
	v_mul_f32_e32 v87, 0xbfb8aa3b, v87
	v_pk_add_f32 v[82:83], v[82:83], v[106:107]
	v_mul_f32_e32 v84, 0xbfb8aa3b, v84
	v_mul_f32_e32 v86, 0xbfb8aa3b, v86
	v_mul_f32_e32 v81, 0xbfb8aa3b, v81
	v_exp_f32_e32 v85, v85
	v_exp_f32_e32 v87, v87
	v_mul_f32_e32 v80, 0xbfb8aa3b, v80
	v_mul_f32_e32 v83, 0xbfb8aa3b, v83
	v_exp_f32_e32 v84, v84
	v_exp_f32_e32 v86, v86
	v_exp_f32_e32 v81, v81
	v_mul_f32_e32 v82, 0xbfb8aa3b, v82
	v_exp_f32_e32 v80, v80
	v_exp_f32_e32 v83, v83
	v_exp_f32_e32 v82, v82
	v_add_f32_e32 v85, 1.0, v85
	v_add_f32_e32 v87, 1.0, v87
	v_add_f32_e32 v84, 1.0, v84
	v_add_f32_e32 v86, 1.0, v86
	v_add_f32_e32 v81, 1.0, v81
	v_rcp_f32_e32 v85, v85
	v_rcp_f32_e32 v87, v87
	v_add_f32_e32 v80, 1.0, v80
	v_add_f32_e32 v83, 1.0, v83
	v_rcp_f32_e32 v84, v84
	v_rcp_f32_e32 v86, v86
	v_rcp_f32_e32 v81, v81
	v_add_f32_e32 v82, 1.0, v82
	v_rcp_f32_e32 v80, v80
	v_rcp_f32_e32 v83, v83
	v_rcp_f32_e32 v82, v82
	s_waitcnt vmcnt(1)
; __device__ __forceinline__ u32x4 pack8(f32x4 v0, f32x4 v1) { u32x4 w; w.x = cvt_pk_bf16(v0[0], v0[1]); w.y = cvt_pk_bf16(v0[2], v0[3]); w.z = cvt_pk_bf16(v1[0], v1[1]); w.w = cvt_pk_bf16(v1[2], v1[3]); return w; }
; __device__ __forceinline__ float sigmoidf_(float x) { return __builtin_amdgcn_rcpf(1.f + __builtin_amdgcn_exp2f(-1.4426950408889634f * x)); }
;     __device__ __forceinline__ void operator()(EPI_ARGS) const {
;     ...
;                 for (int m = 0; m < 4; ++m) { const int row = EPI_ROW(ai, m); const u32x4 yv = *(const u32x4*)(Y + (size_t)row * 1024 + col0);
;                     f32x4 v0 = acc[ai][bj][m][0] + b0, v1 = acc[ai][bj][m][1] + b1;
;                     v0[0] = __uint_as_float(yv.x << 16) * sigmoidf_(v0[0]); v0[1] = __uint_as_float(yv.x & 0xffff0000u) * sigmoidf_(v0[1]);
;                     v0[2] = __uint_as_float(yv.y << 16) * sigmoidf_(v0[2]); v0[3] = __uint_as_float(yv.y & 0xffff0000u) * sigmoidf_(v0[3]);
;                     v1[0] = __uint_as_float(yv.z << 16) * sigmoidf_(v1[0]); v1[1] = __uint_as_float(yv.z & 0xffff0000u) * sigmoidf_(v1[1]);
;                     v1[2] = __uint_as_float(yv.w << 16) * sigmoidf_(v1[2]); v1[3] = __uint_as_float(yv.w & 0xffff0000u) * sigmoidf_(v1[3]);
;                     *(u32x4*)(MIX + (size_t)row * 2048 + 1024 + col0) = pack8(v0, v1);
;                     float ss = (v0[0] * v0[0] + v0[1] * v0[1]) + (v0[2] * v0[2] + v0[3] * v0[3]) + (v1[0] * v1[0] + v1[1] * v1[1]) + (v1[2] * v1[2] + v1[3] * v1[3]);
;                     ss += __shfl_xor(ss, 16); ss += __shfl_xor(ss, 32);
;                     if (fq == 0) atomicAdd(rsq + row, ss); } }
	v_and_b32_e32 v103, 0xffff0000, v170
	v_and_b32_e32 v119, 0xffff0000, v171
	v_lshlrev_b32_e32 v102, 16, v170
	v_lshlrev_b32_e32 v118, 16, v171
	v_and_b32_e32 v127, 0xffff0000, v172
	v_mul_f32_e32 v85, v85, v103
	v_mul_f32_e32 v87, v87, v119
	v_lshlrev_b32_e32 v126, 16, v172
	v_and_b32_e32 v163, 0xffff0000, v173
	v_mul_f32_e32 v84, v84, v102
	v_mul_f32_e32 v86, v86, v118
	v_mul_f32_e32 v81, v81, v127
	v_cvt_pk_bf16_f32 v170, v84, v85
	v_mul_f32_e32 v85, v85, v85
	v_mul_f32_e32 v102, v87, v87
	v_lshlrev_b32_e32 v147, 16, v173
	v_mul_f32_e32 v80, v80, v126
	v_mul_f32_e32 v83, v83, v163
	v_mul_f32_e32 v103, v81, v81
	v_fmac_f32_e32 v85, v84, v84
	v_fmac_f32_e32 v102, v86, v86
	v_mul_f32_e32 v82, v82, v147
	v_mul_f32_e32 v118, v83, v83
	v_fmac_f32_e32 v103, v80, v80
	v_add_f32_e32 v84, v85, v102
	v_add_f32_e32 v84, v103, v84
	v_fmac_f32_e32 v118, v82, v82
	v_add_f32_e32 v84, v118, v84
	ds_bpermute_b32 v85, v134, v84
	v_cvt_pk_bf16_f32 v171, v86, v87
	v_cvt_pk_bf16_f32 v172, v80, v81
	v_lshlrev_b64 v[80:81], 12, v[94:95]
	v_lshl_add_u64 v[80:81], s[58:59], 0, v[80:81]
	s_waitcnt lgkmcnt(0)
	v_add_f32_e32 v84, v84, v85
	ds_bpermute_b32 v85, v135, v84
	v_cvt_pk_bf16_f32 v173, v82, v83
	v_lshl_add_u64 v[82:83], v[80:81], 0, v[144:145]
	v_lshl_add_u64 v[80:81], v[94:95], 2, s[64:65]
	global_store_dwordx4 v[82:83], v[170:173], off offset:2048
	s_waitcnt lgkmcnt(0)
	v_add_f32_e32 v176, v84, v85
	v_mov_b32_e32 v178, v80
	v_mov_b32_e32 v179, v81
	v_add_u32_e32 v86, 0xa0, v146
	v_ashrrev_i32_e32 v87, 31, v86
	s_waitcnt lgkmcnt(0)
	v_lshlrev_b64 v[84:85], 11, v[86:87]
	v_lshl_add_u64 v[84:85], s[88:89], 0, v[84:85]
	v_lshl_add_u64 v[84:85], v[84:85], 0, v[144:145]
	global_load_dwordx4 v[170:173], v[84:85], off
	s_and_saveexec_b64 s[10:11], s[4:5]
	global_atomic_add_f32 v[178:179], v176, off
	s_mov_b64 exec, s[10:11]
	v_pk_add_f32 v[78:79], v[78:79], v[110:111]
	v_pk_add_f32 v[76:77], v[76:77], v[108:109]
	v_pk_add_f32 v[72:73], v[72:73], v[104:105]
	v_mul_f32_e32 v77, 0xbfb8aa3b, v77
	v_mul_f32_e32 v79, 0xbfb8aa3b, v79
	v_pk_add_f32 v[74:75], v[74:75], v[106:107]
	v_mul_f32_e32 v76, 0xbfb8aa3b, v76
	v_mul_f32_e32 v78, 0xbfb8aa3b, v78
	v_mul_f32_e32 v73, 0xbfb8aa3b, v73
	v_exp_f32_e32 v77, v77
	v_exp_f32_e32 v79, v79
	v_mul_f32_e32 v72, 0xbfb8aa3b, v72
	v_mul_f32_e32 v75, 0xbfb8aa3b, v75
	v_exp_f32_e32 v76, v76
	v_exp_f32_e32 v78, v78
	v_exp_f32_e32 v73, v73
	v_mul_f32_e32 v74, 0xbfb8aa3b, v74
	v_exp_f32_e32 v72, v72
	v_exp_f32_e32 v75, v75
	v_exp_f32_e32 v74, v74
	v_add_f32_e32 v77, 1.0, v77
	v_add_f32_e32 v79, 1.0, v79
	v_add_f32_e32 v76, 1.0, v76
	v_add_f32_e32 v78, 1.0, v78
	v_add_f32_e32 v73, 1.0, v73
	v_rcp_f32_e32 v77, v77
	v_rcp_f32_e32 v79, v79
	v_add_f32_e32 v72, 1.0, v72
	v_add_f32_e32 v75, 1.0, v75
	v_rcp_f32_e32 v76, v76
	v_rcp_f32_e32 v78, v78
	v_rcp_f32_e32 v73, v73
	v_add_f32_e32 v74, 1.0, v74
	v_rcp_f32_e32 v72, v72
	v_rcp_f32_e32 v75, v75
	v_rcp_f32_e32 v74, v74
	s_waitcnt vmcnt(1)
	v_and_b32_e32 v95, 0xffff0000, v170
	v_and_b32_e32 v103, 0xffff0000, v171
	v_lshlrev_b32_e32 v94, 16, v170
	v_lshlrev_b32_e32 v102, 16, v171
	v_and_b32_e32 v119, 0xffff0000, v172
	v_mul_f32_e32 v77, v77, v95
	v_mul_f32_e32 v79, v79, v103
	v_lshlrev_b32_e32 v118, 16, v172
	v_and_b32_e32 v127, 0xffff0000, v173
	v_mul_f32_e32 v76, v76, v94
	v_mul_f32_e32 v78, v78, v102
	v_mul_f32_e32 v73, v73, v119
	v_cvt_pk_bf16_f32 v170, v76, v77
	v_mul_f32_e32 v77, v77, v77
	v_mul_f32_e32 v94, v79, v79
	v_lshlrev_b32_e32 v126, 16, v173
	v_mul_f32_e32 v72, v72, v118
	v_mul_f32_e32 v75, v75, v127
	v_mul_f32_e32 v95, v73, v73
	v_fmac_f32_e32 v77, v76, v76
	v_fmac_f32_e32 v94, v78, v78
	v_mul_f32_e32 v74, v74, v126
	v_mul_f32_e32 v102, v75, v75
	v_fmac_f32_e32 v95, v72, v72
	v_add_f32_e32 v76, v77, v94
	v_add_f32_e32 v76, v95, v76
	v_fmac_f32_e32 v102, v74, v74
	v_add_f32_e32 v76, v102, v76
	ds_bpermute_b32 v77, v134, v76
	v_cvt_pk_bf16_f32 v171, v78, v79
	v_cvt_pk_bf16_f32 v172, v72, v73
	v_lshlrev_b64 v[72:73], 12, v[86:87]
	v_lshl_add_u64 v[72:73], s[58:59], 0, v[72:73]
	s_waitcnt lgkmcnt(0)
	v_add_f32_e32 v76, v76, v77
	ds_bpermute_b32 v77, v135, v76
	v_cvt_pk_bf16_f32 v173, v74, v75
	v_lshl_add_u64 v[74:75], v[72:73], 0, v[144:145]
	v_lshl_add_u64 v[72:73], v[86:87], 2, s[64:65]
	global_store_dwordx4 v[74:75], v[170:173], off offset:2048
	s_waitcnt lgkmcnt(0)
	v_add_f32_e32 v176, v76, v77
	v_mov_b32_e32 v178, v72
	v_mov_b32_e32 v179, v73
	v_add_u32_e32 v76, 0xb0, v146
	s_waitcnt lgkmcnt(0)
	v_ashrrev_i32_e32 v77, 31, v76
	v_lshlrev_b64 v[78:79], 11, v[76:77]
	v_lshl_add_u64 v[78:79], s[88:89], 0, v[78:79]
	v_lshl_add_u64 v[78:79], v[78:79], 0, v[144:145]
	global_load_dwordx4 v[170:173], v[78:79], off
	s_and_saveexec_b64 s[10:11], s[4:5]
	global_atomic_add_f32 v[178:179], v176, off
	s_mov_b64 exec, s[10:11]
	v_pk_add_f32 v[70:71], v[70:71], v[110:111]
	v_pk_add_f32 v[68:69], v[68:69], v[108:109]
	v_pk_add_f32 v[66:67], v[66:67], v[106:107]
	v_pk_add_f32 v[64:65], v[64:65], v[104:105]
	v_mul_f32_e32 v69, 0xbfb8aa3b, v69
	v_mul_f32_e32 v71, 0xbfb8aa3b, v71
	v_mul_f32_e32 v68, 0xbfb8aa3b, v68
	v_mul_f32_e32 v70, 0xbfb8aa3b, v70
	v_mul_f32_e32 v65, 0xbfb8aa3b, v65
	v_mul_f32_e32 v66, 0xbfb8aa3b, v66
	v_mul_f32_e32 v67, 0xbfb8aa3b, v67
	v_exp_f32_e32 v69, v69
	v_exp_f32_e32 v71, v71
	v_mul_f32_e32 v64, 0xbfb8aa3b, v64
	v_exp_f32_e32 v68, v68
	v_exp_f32_e32 v70, v70
	v_exp_f32_e32 v65, v65
	v_exp_f32_e32 v66, v66
	v_exp_f32_e32 v67, v67
	v_exp_f32_e32 v64, v64
	v_add_f32_e32 v69, 1.0, v69
	v_add_f32_e32 v71, 1.0, v71
	v_add_f32_e32 v68, 1.0, v68
	v_add_f32_e32 v70, 1.0, v70
	v_add_f32_e32 v65, 1.0, v65
	v_add_f32_e32 v66, 1.0, v66
	v_add_f32_e32 v67, 1.0, v67
	v_rcp_f32_e32 v69, v69
	v_rcp_f32_e32 v71, v71
	v_add_f32_e32 v64, 1.0, v64
	v_rcp_f32_e32 v68, v68
	v_rcp_f32_e32 v70, v70
	v_rcp_f32_e32 v65, v65
	v_rcp_f32_e32 v66, v66
	v_rcp_f32_e32 v67, v67
	v_rcp_f32_e32 v64, v64
	s_waitcnt vmcnt(1)
; __device__ __forceinline__ u32x4 pack8(f32x4 v0, f32x4 v1) { u32x4 w; w.x = cvt_pk_bf16(v0[0], v0[1]); w.y = cvt_pk_bf16(v0[2], v0[3]); w.z = cvt_pk_bf16(v1[0], v1[1]); w.w = cvt_pk_bf16(v1[2], v1[3]); return w; }
; __device__ __forceinline__ float sigmoidf_(float x) { return __builtin_amdgcn_rcpf(1.f + __builtin_amdgcn_exp2f(-1.4426950408889634f * x)); }
;     __device__ __forceinline__ void operator()(EPI_ARGS) const {
;     ...
;         for (int bj = 0; bj < 2; ++bj) { const int col0 = EPI_COL(bj); const f32x4 b0 = *(const f32x4*)(bias + col0), b1 = *(const f32x4*)(bias + col0 + 4);
; #pragma unroll
;             for (int ai = 0; ai < 2; ++ai)
; #pragma unroll
;                 for (int m = 0; m < 4; ++m) { const int row = EPI_ROW(ai, m); const u32x4 yv = *(const u32x4*)(Y + (size_t)row * 1024 + col0);
;                     f32x4 v0 = acc[ai][bj][m][0] + b0, v1 = acc[ai][bj][m][1] + b1;
;                     v0[0] = __uint_as_float(yv.x << 16) * sigmoidf_(v0[0]); v0[1] = __uint_as_float(yv.x & 0xffff0000u) * sigmoidf_(v0[1]);
;                     v0[2] = __uint_as_float(yv.y << 16) * sigmoidf_(v0[2]); v0[3] = __uint_as_float(yv.y & 0xffff0000u) * sigmoidf_(v0[3]);
;                     v1[0] = __uint_as_float(yv.z << 16) * sigmoidf_(v1[0]); v1[1] = __uint_as_float(yv.z & 0xffff0000u) * sigmoidf_(v1[1]);
;                     v1[2] = __uint_as_float(yv.w << 16) * sigmoidf_(v1[2]); v1[3] = __uint_as_float(yv.w & 0xffff0000u) * sigmoidf_(v1[3]);
;                     *(u32x4*)(MIX + (size_t)row * 2048 + 1024 + col0) = pack8(v0, v1);
;                     float ss = (v0[0] * v0[0] + v0[1] * v0[1]) + (v0[2] * v0[2] + v0[3] * v0[3]) + (v1[0] * v1[0] + v1[1] * v1[1]) + (v1[2] * v1[2] + v1[3] * v1[3]);
;                     ss += __shfl_xor(ss, 16); ss += __shfl_xor(ss, 32);
;                     if (fq == 0) atomicAdd(rsq + row, ss); } }
	v_and_b32_e32 v87, 0xffff0000, v170
	v_and_b32_e32 v95, 0xffff0000, v171
	v_lshlrev_b32_e32 v86, 16, v170
	v_lshlrev_b32_e32 v94, 16, v171
	v_and_b32_e32 v103, 0xffff0000, v172
	v_lshlrev_b32_e32 v104, 16, v173
	v_and_b32_e32 v105, 0xffff0000, v173
	v_mul_f32_e32 v69, v69, v87
	v_mul_f32_e32 v71, v71, v95
	v_lshlrev_b32_e32 v102, 16, v172
	v_mul_f32_e32 v68, v68, v86
	v_mul_f32_e32 v70, v70, v94
	v_mul_f32_e32 v65, v65, v103
	v_mul_f32_e32 v86, v66, v104
	v_mul_f32_e32 v87, v67, v105
	v_cvt_pk_bf16_f32 v66, v68, v69
	v_mul_f32_e32 v67, v69, v69
	v_mul_f32_e32 v69, v71, v71
	v_mul_f32_e32 v64, v64, v102
	v_mul_f32_e32 v94, v65, v65
	v_fmac_f32_e32 v67, v68, v68
	v_fmac_f32_e32 v69, v70, v70
	v_mul_f32_e32 v95, v87, v87
	v_fmac_f32_e32 v94, v64, v64
	v_add_f32_e32 v67, v67, v69
	v_add_f32_e32 v67, v94, v67
	v_fmac_f32_e32 v95, v86, v86
	v_add_f32_e32 v94, v95, v67
	ds_bpermute_b32 v95, v134, v94
	v_cvt_pk_bf16_f32 v67, v70, v71
	v_cvt_pk_bf16_f32 v68, v64, v65
	v_lshlrev_b64 v[70:71], 12, v[76:77]
	v_lshl_add_u64 v[70:71], s[58:59], 0, v[70:71]
	s_waitcnt lgkmcnt(0)
	v_add_f32_e32 v64, v94, v95
	ds_bpermute_b32 v65, v135, v64
	v_cvt_pk_bf16_f32 v69, v86, v87
	v_lshl_add_u64 v[86:87], v[70:71], 0, v[144:145]
	v_lshl_add_u64 v[76:77], v[76:77], 2, s[64:65]
	global_store_dwordx4 v[86:87], v[66:69], off offset:2048
	s_and_saveexec_b64 s[10:11], s[4:5]
	s_cbranch_execz .LBB0_615
	s_waitcnt lgkmcnt(0)
	v_add_f32_e32 v64, v64, v65
	global_atomic_add_f32 v[76:77], v64, off
.LBB0_615:
	s_or_b64 exec, exec, s[10:11]
	global_load_dwordx4 v[68:71], v[140:141], off offset:512
	s_waitcnt lgkmcnt(0)
	global_load_dwordx4 v[64:67], v[140:141], off offset:528
	global_load_dwordx4 v[102:105], v[142:143], off offset:256
	s_waitcnt vmcnt(2)
	v_pk_add_f32 v[62:63], v[62:63], v[70:71]
	v_pk_add_f32 v[60:61], v[60:61], v[68:69]
	s_waitcnt vmcnt(1)
	v_pk_add_f32 v[56:57], v[56:57], v[64:65]
	v_mul_f32_e32 v61, 0xbfb8aa3b, v61
	v_mul_f32_e32 v63, 0xbfb8aa3b, v63
	v_pk_add_f32 v[58:59], v[58:59], v[66:67]
	v_mul_f32_e32 v60, 0xbfb8aa3b, v60
	v_mul_f32_e32 v62, 0xbfb8aa3b, v62
	v_mul_f32_e32 v56, 0xbfb8aa3b, v56
	v_mul_f32_e32 v57, 0xbfb8aa3b, v57
	v_exp_f32_e32 v61, v61
	v_exp_f32_e32 v63, v63
	v_mul_f32_e32 v58, 0xbfb8aa3b, v58
	v_mul_f32_e32 v59, 0xbfb8aa3b, v59
	v_exp_f32_e32 v60, v60
	v_exp_f32_e32 v62, v62
	v_exp_f32_e32 v56, v56
	v_exp_f32_e32 v57, v57
	v_exp_f32_e32 v58, v58
	v_exp_f32_e32 v59, v59
	v_add_f32_e32 v61, 1.0, v61
	v_add_f32_e32 v63, 1.0, v63
	v_add_f32_e32 v60, 1.0, v60
	v_add_f32_e32 v62, 1.0, v62
	v_add_f32_e32 v56, 1.0, v56
	v_add_f32_e32 v57, 1.0, v57
	v_rcp_f32_e32 v61, v61
	v_rcp_f32_e32 v63, v63
	v_add_f32_e32 v58, 1.0, v58
	v_add_f32_e32 v59, 1.0, v59
	v_rcp_f32_e32 v60, v60
	v_rcp_f32_e32 v62, v62
	v_rcp_f32_e32 v56, v56
	v_rcp_f32_e32 v57, v57
	v_rcp_f32_e32 v58, v58
	v_rcp_f32_e32 v59, v59
	s_waitcnt vmcnt(0)
	v_lshlrev_b32_e32 v94, 16, v102
	v_and_b32_e32 v95, 0xffff0000, v102
	v_lshlrev_b32_e32 v102, 16, v103
	v_and_b32_e32 v103, 0xffff0000, v103
	v_lshlrev_b32_e32 v106, 16, v104
	v_and_b32_e32 v104, 0xffff0000, v104
	v_mul_f32_e32 v61, v61, v95
	v_mul_f32_e32 v63, v63, v103
	v_lshlrev_b32_e32 v107, 16, v105
	v_and_b32_e32 v105, 0xffff0000, v105
	v_mul_f32_e32 v60, v60, v94
	v_mul_f32_e32 v62, v62, v102
	v_mul_f32_e32 v94, v56, v106
	v_mul_f32_e32 v95, v57, v104
	v_mul_f32_e32 v56, v61, v61
	v_mul_f32_e32 v57, v63, v63
	v_mul_f32_e32 v102, v58, v107
	v_mul_f32_e32 v103, v59, v105
	v_mul_f32_e32 v58, v95, v95
	v_fmac_f32_e32 v56, v60, v60
	v_fmac_f32_e32 v57, v62, v62
	v_mul_f32_e32 v59, v103, v103
	v_fmac_f32_e32 v58, v94, v94
	v_add_f32_e32 v56, v56, v57
	v_add_f32_e32 v56, v56, v58
	v_fmac_f32_e32 v59, v102, v102
	v_add_f32_e32 v56, v59, v56
	ds_bpermute_b32 v57, v134, v56
	v_cvt_pk_bf16_f32 v58, v60, v61
	v_cvt_pk_bf16_f32 v59, v62, v63
	v_cvt_pk_bf16_f32 v60, v94, v95
	v_cvt_pk_bf16_f32 v61, v102, v103
	s_waitcnt lgkmcnt(0)
	v_add_f32_e32 v56, v56, v57
	ds_bpermute_b32 v57, v135, v56
	global_store_dwordx4 v[128:129], v[58:61], off offset:2304
	s_waitcnt lgkmcnt(0)
	v_add_f32_e32 v176, v56, v57
	v_mov_b32_e32 v178, v130
	v_mov_b32_e32 v179, v131
	s_waitcnt lgkmcnt(0)
	global_load_dwordx4 v[56:59], v[132:133], off offset:256
	s_and_saveexec_b64 s[10:11], s[4:5]
	global_atomic_add_f32 v[178:179], v176, off
	s_mov_b64 exec, s[10:11]
	v_pk_add_f32 v[54:55], v[54:55], v[70:71]
	v_pk_add_f32 v[52:53], v[52:53], v[68:69]
	v_pk_add_f32 v[48:49], v[48:49], v[64:65]
	v_mul_f32_e32 v53, 0xbfb8aa3b, v53
	v_mul_f32_e32 v55, 0xbfb8aa3b, v55
	v_pk_add_f32 v[50:51], v[50:51], v[66:67]
	v_mul_f32_e32 v52, 0xbfb8aa3b, v52
	v_mul_f32_e32 v54, 0xbfb8aa3b, v54
	v_mul_f32_e32 v48, 0xbfb8aa3b, v48
	v_mul_f32_e32 v49, 0xbfb8aa3b, v49
	v_exp_f32_e32 v53, v53
	v_exp_f32_e32 v55, v55
	v_mul_f32_e32 v50, 0xbfb8aa3b, v50
	v_mul_f32_e32 v51, 0xbfb8aa3b, v51
	v_exp_f32_e32 v52, v52
	v_exp_f32_e32 v54, v54
	v_exp_f32_e32 v48, v48
	v_exp_f32_e32 v49, v49
	v_exp_f32_e32 v50, v50
	v_exp_f32_e32 v51, v51
	v_add_f32_e32 v53, 1.0, v53
	v_add_f32_e32 v55, 1.0, v55
	v_add_f32_e32 v52, 1.0, v52
	v_add_f32_e32 v54, 1.0, v54
	v_add_f32_e32 v48, 1.0, v48
	v_add_f32_e32 v49, 1.0, v49
	v_rcp_f32_e32 v53, v53
	v_rcp_f32_e32 v55, v55
	v_add_f32_e32 v50, 1.0, v50
	v_add_f32_e32 v51, 1.0, v51
	v_rcp_f32_e32 v52, v52
	v_rcp_f32_e32 v54, v54
	v_rcp_f32_e32 v48, v48
	v_rcp_f32_e32 v49, v49
	v_rcp_f32_e32 v50, v50
	v_rcp_f32_e32 v51, v51
	s_waitcnt vmcnt(1)
; __device__ __forceinline__ u32x4 pack8(f32x4 v0, f32x4 v1) { u32x4 w; w.x = cvt_pk_bf16(v0[0], v0[1]); w.y = cvt_pk_bf16(v0[2], v0[3]); w.z = cvt_pk_bf16(v1[0], v1[1]); w.w = cvt_pk_bf16(v1[2], v1[3]); return w; }
; __device__ __forceinline__ float sigmoidf_(float x) { return __builtin_amdgcn_rcpf(1.f + __builtin_amdgcn_exp2f(-1.4426950408889634f * x)); }
;     __device__ __forceinline__ void operator()(EPI_ARGS) const {
;     ...
;                 for (int m = 0; m < 4; ++m) { const int row = EPI_ROW(ai, m); const u32x4 yv = *(const u32x4*)(Y + (size_t)row * 1024 + col0);
;                     f32x4 v0 = acc[ai][bj][m][0] + b0, v1 = acc[ai][bj][m][1] + b1;
;                     v0[0] = __uint_as_float(yv.x << 16) * sigmoidf_(v0[0]); v0[1] = __uint_as_float(yv.x & 0xffff0000u) * sigmoidf_(v0[1]);
;                     v0[2] = __uint_as_float(yv.y << 16) * sigmoidf_(v0[2]); v0[3] = __uint_as_float(yv.y & 0xffff0000u) * sigmoidf_(v0[3]);
;                     v1[0] = __uint_as_float(yv.z << 16) * sigmoidf_(v1[0]); v1[1] = __uint_as_float(yv.z & 0xffff0000u) * sigmoidf_(v1[1]);
;                     v1[2] = __uint_as_float(yv.w << 16) * sigmoidf_(v1[2]); v1[3] = __uint_as_float(yv.w & 0xffff0000u) * sigmoidf_(v1[3]);
;                     *(u32x4*)(MIX + (size_t)row * 2048 + 1024 + col0) = pack8(v0, v1);
;                     float ss = (v0[0] * v0[0] + v0[1] * v0[1]) + (v0[2] * v0[2] + v0[3] * v0[3]) + (v1[0] * v1[0] + v1[1] * v1[1]) + (v1[2] * v1[2] + v1[3] * v1[3]);
;                     ss += __shfl_xor(ss, 16); ss += __shfl_xor(ss, 32);
;                     if (fq == 0) atomicAdd(rsq + row, ss); } }
	v_lshlrev_b32_e32 v60, 16, v56
	v_and_b32_e32 v56, 0xffff0000, v56
	v_lshlrev_b32_e32 v61, 16, v57
	v_and_b32_e32 v57, 0xffff0000, v57
	v_lshlrev_b32_e32 v62, 16, v58
	v_and_b32_e32 v58, 0xffff0000, v58
	v_mul_f32_e32 v53, v53, v56
	v_mul_f32_e32 v55, v55, v57
	v_lshlrev_b32_e32 v63, 16, v59
	v_and_b32_e32 v59, 0xffff0000, v59
	v_mul_f32_e32 v52, v52, v60
	v_mul_f32_e32 v54, v54, v61
	v_mul_f32_e32 v56, v48, v62
	v_mul_f32_e32 v57, v49, v58
	v_mul_f32_e32 v48, v53, v53
	v_mul_f32_e32 v49, v55, v55
	v_mul_f32_e32 v58, v50, v63
	v_mul_f32_e32 v59, v51, v59
	v_mul_f32_e32 v50, v57, v57
	v_fmac_f32_e32 v48, v52, v52
	v_fmac_f32_e32 v49, v54, v54
	v_mul_f32_e32 v51, v59, v59
	v_fmac_f32_e32 v50, v56, v56
	v_add_f32_e32 v48, v48, v49
	v_add_f32_e32 v48, v50, v48
	v_fmac_f32_e32 v51, v58, v58
	v_add_f32_e32 v48, v51, v48
	ds_bpermute_b32 v49, v134, v48
	v_cvt_pk_bf16_f32 v50, v52, v53
	v_cvt_pk_bf16_f32 v51, v54, v55
	v_cvt_pk_bf16_f32 v52, v56, v57
	v_cvt_pk_bf16_f32 v53, v58, v59
	s_waitcnt lgkmcnt(0)
	v_add_f32_e32 v48, v48, v49
	ds_bpermute_b32 v49, v135, v48
	global_store_dwordx4 v[122:123], v[50:53], off offset:2304
	s_waitcnt lgkmcnt(0)
	v_add_f32_e32 v176, v48, v49
	v_mov_b32_e32 v178, v120
	v_mov_b32_e32 v179, v121
	s_waitcnt lgkmcnt(0)
	global_load_dwordx4 v[48:51], v[124:125], off offset:256
	s_and_saveexec_b64 s[10:11], s[4:5]
	global_atomic_add_f32 v[178:179], v176, off
	s_mov_b64 exec, s[10:11]
	v_pk_add_f32 v[46:47], v[46:47], v[70:71]
	v_pk_add_f32 v[44:45], v[44:45], v[68:69]
	v_pk_add_f32 v[40:41], v[40:41], v[64:65]
	v_mul_f32_e32 v45, 0xbfb8aa3b, v45
	v_mul_f32_e32 v47, 0xbfb8aa3b, v47
	v_pk_add_f32 v[42:43], v[42:43], v[66:67]
	v_mul_f32_e32 v44, 0xbfb8aa3b, v44
	v_mul_f32_e32 v46, 0xbfb8aa3b, v46
	v_mul_f32_e32 v40, 0xbfb8aa3b, v40
	v_mul_f32_e32 v41, 0xbfb8aa3b, v41
	v_exp_f32_e32 v45, v45
	v_exp_f32_e32 v47, v47
	v_mul_f32_e32 v42, 0xbfb8aa3b, v42
	v_mul_f32_e32 v43, 0xbfb8aa3b, v43
	v_exp_f32_e32 v44, v44
	v_exp_f32_e32 v46, v46
	v_exp_f32_e32 v40, v40
	v_exp_f32_e32 v41, v41
	v_exp_f32_e32 v42, v42
	v_exp_f32_e32 v43, v43
	v_add_f32_e32 v45, 1.0, v45
	v_add_f32_e32 v47, 1.0, v47
	v_add_f32_e32 v44, 1.0, v44
	v_add_f32_e32 v46, 1.0, v46
	v_add_f32_e32 v40, 1.0, v40
	v_add_f32_e32 v41, 1.0, v41
	v_rcp_f32_e32 v45, v45
	v_rcp_f32_e32 v47, v47
	v_add_f32_e32 v42, 1.0, v42
	v_add_f32_e32 v43, 1.0, v43
	v_rcp_f32_e32 v44, v44
	v_rcp_f32_e32 v46, v46
	v_rcp_f32_e32 v40, v40
	v_rcp_f32_e32 v41, v41
	v_rcp_f32_e32 v42, v42
	v_rcp_f32_e32 v43, v43
	s_waitcnt vmcnt(1)
	v_lshlrev_b32_e32 v52, 16, v48
	v_and_b32_e32 v48, 0xffff0000, v48
	v_lshlrev_b32_e32 v53, 16, v49
	v_and_b32_e32 v49, 0xffff0000, v49
	v_lshlrev_b32_e32 v54, 16, v50
	v_and_b32_e32 v50, 0xffff0000, v50
	v_mul_f32_e32 v45, v45, v48
	v_mul_f32_e32 v47, v47, v49
	v_lshlrev_b32_e32 v55, 16, v51
	v_and_b32_e32 v51, 0xffff0000, v51
	v_mul_f32_e32 v44, v44, v52
	v_mul_f32_e32 v46, v46, v53
	v_mul_f32_e32 v48, v40, v54
	v_mul_f32_e32 v49, v41, v50
	v_mul_f32_e32 v40, v45, v45
	v_mul_f32_e32 v41, v47, v47
	v_mul_f32_e32 v50, v42, v55
	v_mul_f32_e32 v51, v43, v51
	v_mul_f32_e32 v42, v49, v49
	v_fmac_f32_e32 v40, v44, v44
	v_fmac_f32_e32 v41, v46, v46
	v_mul_f32_e32 v43, v51, v51
	v_fmac_f32_e32 v42, v48, v48
	v_add_f32_e32 v40, v40, v41
	v_add_f32_e32 v40, v42, v40
	v_fmac_f32_e32 v43, v50, v50
	v_add_f32_e32 v40, v43, v40
	ds_bpermute_b32 v41, v134, v40
	v_cvt_pk_bf16_f32 v42, v44, v45
	v_cvt_pk_bf16_f32 v43, v46, v47
	v_cvt_pk_bf16_f32 v44, v48, v49
	v_cvt_pk_bf16_f32 v45, v50, v51
	s_waitcnt lgkmcnt(0)
	v_add_f32_e32 v40, v40, v41
	ds_bpermute_b32 v41, v135, v40
	global_store_dwordx4 v[114:115], v[42:45], off offset:2304
	s_waitcnt lgkmcnt(0)
	v_add_f32_e32 v176, v40, v41
	v_mov_b32_e32 v178, v112
	v_mov_b32_e32 v179, v113
	s_waitcnt lgkmcnt(0)
	global_load_dwordx4 v[40:43], v[116:117], off offset:256
	s_and_saveexec_b64 s[10:11], s[4:5]
	global_atomic_add_f32 v[178:179], v176, off
	s_mov_b64 exec, s[10:11]
	v_pk_add_f32 v[38:39], v[38:39], v[70:71]
	v_pk_add_f32 v[36:37], v[36:37], v[68:69]
	v_pk_add_f32 v[32:33], v[32:33], v[64:65]
	v_mul_f32_e32 v37, 0xbfb8aa3b, v37
	v_mul_f32_e32 v39, 0xbfb8aa3b, v39
	v_pk_add_f32 v[34:35], v[34:35], v[66:67]
	v_mul_f32_e32 v36, 0xbfb8aa3b, v36
	v_mul_f32_e32 v38, 0xbfb8aa3b, v38
	v_mul_f32_e32 v32, 0xbfb8aa3b, v32
	v_mul_f32_e32 v33, 0xbfb8aa3b, v33
	v_exp_f32_e32 v37, v37
	v_exp_f32_e32 v39, v39
	v_mul_f32_e32 v34, 0xbfb8aa3b, v34
	v_mul_f32_e32 v35, 0xbfb8aa3b, v35
	v_exp_f32_e32 v36, v36
	v_exp_f32_e32 v38, v38
	v_exp_f32_e32 v32, v32
	v_exp_f32_e32 v33, v33
	v_exp_f32_e32 v34, v34
	v_exp_f32_e32 v35, v35
	v_add_f32_e32 v37, 1.0, v37
	v_add_f32_e32 v39, 1.0, v39
	v_add_f32_e32 v36, 1.0, v36
	v_add_f32_e32 v38, 1.0, v38
	v_add_f32_e32 v32, 1.0, v32
	v_add_f32_e32 v33, 1.0, v33
	v_rcp_f32_e32 v37, v37
	v_rcp_f32_e32 v39, v39
	v_add_f32_e32 v34, 1.0, v34
	v_add_f32_e32 v35, 1.0, v35
	v_rcp_f32_e32 v36, v36
	v_rcp_f32_e32 v38, v38
	v_rcp_f32_e32 v32, v32
	v_rcp_f32_e32 v33, v33
	v_rcp_f32_e32 v34, v34
	v_rcp_f32_e32 v35, v35
	s_waitcnt vmcnt(1)
	v_lshlrev_b32_e32 v44, 16, v40
	v_and_b32_e32 v40, 0xffff0000, v40
	v_lshlrev_b32_e32 v45, 16, v41
	v_and_b32_e32 v41, 0xffff0000, v41
	v_lshlrev_b32_e32 v46, 16, v42
	v_and_b32_e32 v42, 0xffff0000, v42
	v_mul_f32_e32 v37, v37, v40
	v_mul_f32_e32 v39, v39, v41
	v_lshlrev_b32_e32 v47, 16, v43
	v_and_b32_e32 v43, 0xffff0000, v43
	v_mul_f32_e32 v36, v36, v44
	v_mul_f32_e32 v38, v38, v45
	v_mul_f32_e32 v40, v32, v46
	v_mul_f32_e32 v41, v33, v42
	v_mul_f32_e32 v32, v37, v37
	v_mul_f32_e32 v33, v39, v39
	v_mul_f32_e32 v42, v34, v47
	v_mul_f32_e32 v43, v35, v43
	v_mul_f32_e32 v34, v41, v41
	v_fmac_f32_e32 v32, v36, v36
	v_fmac_f32_e32 v33, v38, v38
	v_mul_f32_e32 v35, v43, v43
	v_fmac_f32_e32 v34, v40, v40
	v_add_f32_e32 v32, v32, v33
	v_add_f32_e32 v32, v34, v32
	v_fmac_f32_e32 v35, v42, v42
	v_add_f32_e32 v32, v35, v32
	ds_bpermute_b32 v33, v134, v32
	v_cvt_pk_bf16_f32 v34, v36, v37
	v_cvt_pk_bf16_f32 v35, v38, v39
	v_cvt_pk_bf16_f32 v36, v40, v41
	v_cvt_pk_bf16_f32 v37, v42, v43
	s_waitcnt lgkmcnt(0)
; __device__ __forceinline__ u32x4 pack8(f32x4 v0, f32x4 v1) { u32x4 w; w.x = cvt_pk_bf16(v0[0], v0[1]); w.y = cvt_pk_bf16(v0[2], v0[3]); w.z = cvt_pk_bf16(v1[0], v1[1]); w.w = cvt_pk_bf16(v1[2], v1[3]); return w; }
; __device__ __forceinline__ float sigmoidf_(float x) { return __builtin_amdgcn_rcpf(1.f + __builtin_amdgcn_exp2f(-1.4426950408889634f * x)); }
;     __device__ __forceinline__ void operator()(EPI_ARGS) const {
;     ...
;                 for (int m = 0; m < 4; ++m) { const int row = EPI_ROW(ai, m); const u32x4 yv = *(const u32x4*)(Y + (size_t)row * 1024 + col0);
;                     f32x4 v0 = acc[ai][bj][m][0] + b0, v1 = acc[ai][bj][m][1] + b1;
;                     v0[0] = __uint_as_float(yv.x << 16) * sigmoidf_(v0[0]); v0[1] = __uint_as_float(yv.x & 0xffff0000u) * sigmoidf_(v0[1]);
;                     v0[2] = __uint_as_float(yv.y << 16) * sigmoidf_(v0[2]); v0[3] = __uint_as_float(yv.y & 0xffff0000u) * sigmoidf_(v0[3]);
;                     v1[0] = __uint_as_float(yv.z << 16) * sigmoidf_(v1[0]); v1[1] = __uint_as_float(yv.z & 0xffff0000u) * sigmoidf_(v1[1]);
;                     v1[2] = __uint_as_float(yv.w << 16) * sigmoidf_(v1[2]); v1[3] = __uint_as_float(yv.w & 0xffff0000u) * sigmoidf_(v1[3]);
;                     *(u32x4*)(MIX + (size_t)row * 2048 + 1024 + col0) = pack8(v0, v1);
;                     float ss = (v0[0] * v0[0] + v0[1] * v0[1]) + (v0[2] * v0[2] + v0[3] * v0[3]) + (v1[0] * v1[0] + v1[1] * v1[1]) + (v1[2] * v1[2] + v1[3] * v1[3]);
;                     ss += __shfl_xor(ss, 16); ss += __shfl_xor(ss, 32);
;                     if (fq == 0) atomicAdd(rsq + row, ss); } }
	v_add_f32_e32 v32, v32, v33
	ds_bpermute_b32 v33, v135, v32
	global_store_dwordx4 v[98:99], v[34:37], off offset:2304
	s_waitcnt lgkmcnt(0)
	v_add_f32_e32 v176, v32, v33
	v_mov_b32_e32 v178, v96
	v_mov_b32_e32 v179, v97
	s_waitcnt lgkmcnt(0)
	global_load_dwordx4 v[32:35], v[100:101], off offset:256
	s_and_saveexec_b64 s[10:11], s[4:5]
	global_atomic_add_f32 v[178:179], v176, off
	s_mov_b64 exec, s[10:11]
	v_pk_add_f32 v[30:31], v[30:31], v[70:71]
	v_pk_add_f32 v[28:29], v[28:29], v[68:69]
	v_pk_add_f32 v[24:25], v[24:25], v[64:65]
	v_mul_f32_e32 v29, 0xbfb8aa3b, v29
	v_mul_f32_e32 v31, 0xbfb8aa3b, v31
	v_pk_add_f32 v[26:27], v[26:27], v[66:67]
	v_mul_f32_e32 v28, 0xbfb8aa3b, v28
	v_mul_f32_e32 v30, 0xbfb8aa3b, v30
	v_mul_f32_e32 v24, 0xbfb8aa3b, v24
	v_mul_f32_e32 v25, 0xbfb8aa3b, v25
	v_exp_f32_e32 v29, v29
	v_exp_f32_e32 v31, v31
	v_mul_f32_e32 v26, 0xbfb8aa3b, v26
	v_mul_f32_e32 v27, 0xbfb8aa3b, v27
	v_exp_f32_e32 v28, v28
	v_exp_f32_e32 v30, v30
	v_exp_f32_e32 v24, v24
	v_exp_f32_e32 v25, v25
	v_exp_f32_e32 v26, v26
	v_exp_f32_e32 v27, v27
	v_add_f32_e32 v29, 1.0, v29
	v_add_f32_e32 v31, 1.0, v31
	v_add_f32_e32 v28, 1.0, v28
	v_add_f32_e32 v30, 1.0, v30
	v_add_f32_e32 v24, 1.0, v24
	v_add_f32_e32 v25, 1.0, v25
	v_rcp_f32_e32 v29, v29
	v_rcp_f32_e32 v31, v31
	v_add_f32_e32 v26, 1.0, v26
	v_add_f32_e32 v27, 1.0, v27
	v_rcp_f32_e32 v28, v28
	v_rcp_f32_e32 v30, v30
	v_rcp_f32_e32 v24, v24
	v_rcp_f32_e32 v25, v25
	v_rcp_f32_e32 v26, v26
	v_rcp_f32_e32 v27, v27
	s_waitcnt vmcnt(1)
	v_lshlrev_b32_e32 v36, 16, v32
	v_and_b32_e32 v32, 0xffff0000, v32
	v_lshlrev_b32_e32 v37, 16, v33
	v_and_b32_e32 v33, 0xffff0000, v33
	v_lshlrev_b32_e32 v38, 16, v34
	v_and_b32_e32 v34, 0xffff0000, v34
	v_mul_f32_e32 v29, v29, v32
	v_mul_f32_e32 v31, v31, v33
	v_lshlrev_b32_e32 v39, 16, v35
	v_and_b32_e32 v35, 0xffff0000, v35
	v_mul_f32_e32 v28, v28, v36
	v_mul_f32_e32 v30, v30, v37
	v_mul_f32_e32 v32, v24, v38
	v_mul_f32_e32 v33, v25, v34
	v_mul_f32_e32 v24, v29, v29
	v_mul_f32_e32 v25, v31, v31
	v_mul_f32_e32 v34, v26, v39
	v_mul_f32_e32 v35, v27, v35
	v_mul_f32_e32 v26, v33, v33
	v_fmac_f32_e32 v24, v28, v28
	v_fmac_f32_e32 v25, v30, v30
	v_mul_f32_e32 v27, v35, v35
	v_fmac_f32_e32 v26, v32, v32
	v_add_f32_e32 v24, v24, v25
	v_add_f32_e32 v24, v26, v24
	v_fmac_f32_e32 v27, v34, v34
	v_add_f32_e32 v24, v27, v24
	ds_bpermute_b32 v25, v134, v24
	v_cvt_pk_bf16_f32 v26, v28, v29
	v_cvt_pk_bf16_f32 v27, v30, v31
	v_cvt_pk_bf16_f32 v28, v32, v33
	v_cvt_pk_bf16_f32 v29, v34, v35
	s_waitcnt lgkmcnt(0)
	v_add_f32_e32 v24, v24, v25
	ds_bpermute_b32 v25, v135, v24
	global_store_dwordx4 v[90:91], v[26:29], off offset:2304
	s_waitcnt lgkmcnt(0)
	v_add_f32_e32 v176, v24, v25
	v_mov_b32_e32 v178, v88
	v_mov_b32_e32 v179, v89
	s_waitcnt lgkmcnt(0)
	global_load_dwordx4 v[24:27], v[92:93], off offset:256
	s_and_saveexec_b64 s[10:11], s[4:5]
	global_atomic_add_f32 v[178:179], v176, off
	s_mov_b64 exec, s[10:11]
	v_pk_add_f32 v[22:23], v[22:23], v[70:71]
	v_pk_add_f32 v[20:21], v[20:21], v[68:69]
	v_pk_add_f32 v[16:17], v[16:17], v[64:65]
	v_mul_f32_e32 v21, 0xbfb8aa3b, v21
	v_mul_f32_e32 v23, 0xbfb8aa3b, v23
	v_pk_add_f32 v[18:19], v[18:19], v[66:67]
	v_mul_f32_e32 v20, 0xbfb8aa3b, v20
	v_mul_f32_e32 v22, 0xbfb8aa3b, v22
	v_mul_f32_e32 v16, 0xbfb8aa3b, v16
	v_mul_f32_e32 v17, 0xbfb8aa3b, v17
	v_exp_f32_e32 v21, v21
	v_exp_f32_e32 v23, v23
	v_mul_f32_e32 v18, 0xbfb8aa3b, v18
	v_mul_f32_e32 v19, 0xbfb8aa3b, v19
	v_exp_f32_e32 v20, v20
	v_exp_f32_e32 v22, v22
	v_exp_f32_e32 v16, v16
	v_exp_f32_e32 v17, v17
	v_exp_f32_e32 v18, v18
	v_exp_f32_e32 v19, v19
	v_add_f32_e32 v21, 1.0, v21
	v_add_f32_e32 v23, 1.0, v23
	v_add_f32_e32 v20, 1.0, v20
	v_add_f32_e32 v22, 1.0, v22
	v_add_f32_e32 v16, 1.0, v16
	v_add_f32_e32 v17, 1.0, v17
	v_rcp_f32_e32 v21, v21
	v_rcp_f32_e32 v23, v23
	v_add_f32_e32 v18, 1.0, v18
	v_add_f32_e32 v19, 1.0, v19
	v_rcp_f32_e32 v20, v20
	v_rcp_f32_e32 v22, v22
	v_rcp_f32_e32 v16, v16
	v_rcp_f32_e32 v17, v17
	v_rcp_f32_e32 v18, v18
	v_rcp_f32_e32 v19, v19
	s_waitcnt vmcnt(1)
	v_lshlrev_b32_e32 v28, 16, v24
	v_and_b32_e32 v24, 0xffff0000, v24
	v_lshlrev_b32_e32 v29, 16, v25
	v_and_b32_e32 v25, 0xffff0000, v25
	v_lshlrev_b32_e32 v30, 16, v26
	v_and_b32_e32 v26, 0xffff0000, v26
	v_mul_f32_e32 v21, v21, v24
	v_mul_f32_e32 v23, v23, v25
	v_lshlrev_b32_e32 v31, 16, v27
	v_and_b32_e32 v27, 0xffff0000, v27
	v_mul_f32_e32 v20, v20, v28
	v_mul_f32_e32 v22, v22, v29
	v_mul_f32_e32 v24, v16, v30
	v_mul_f32_e32 v25, v17, v26
	v_mul_f32_e32 v16, v21, v21
	v_mul_f32_e32 v17, v23, v23
	v_mul_f32_e32 v26, v18, v31
	v_mul_f32_e32 v27, v19, v27
	v_mul_f32_e32 v18, v25, v25
	v_fmac_f32_e32 v16, v20, v20
	v_fmac_f32_e32 v17, v22, v22
	v_mul_f32_e32 v19, v27, v27
	v_fmac_f32_e32 v18, v24, v24
	v_add_f32_e32 v16, v16, v17
	v_add_f32_e32 v16, v18, v16
	v_fmac_f32_e32 v19, v26, v26
	v_add_f32_e32 v16, v19, v16
	ds_bpermute_b32 v17, v134, v16
	v_cvt_pk_bf16_f32 v18, v20, v21
	v_cvt_pk_bf16_f32 v19, v22, v23
	v_cvt_pk_bf16_f32 v20, v24, v25
	v_cvt_pk_bf16_f32 v21, v26, v27
	s_waitcnt lgkmcnt(0)
; __device__ __forceinline__ u32x4 pack8(f32x4 v0, f32x4 v1) { u32x4 w; w.x = cvt_pk_bf16(v0[0], v0[1]); w.y = cvt_pk_bf16(v0[2], v0[3]); w.z = cvt_pk_bf16(v1[0], v1[1]); w.w = cvt_pk_bf16(v1[2], v1[3]); return w; }
; __device__ __forceinline__ float sigmoidf_(float x) { return __builtin_amdgcn_rcpf(1.f + __builtin_amdgcn_exp2f(-1.4426950408889634f * x)); }
;     __device__ __forceinline__ void operator()(EPI_ARGS) const {
;     ...
;                 for (int m = 0; m < 4; ++m) { const int row = EPI_ROW(ai, m); const u32x4 yv = *(const u32x4*)(Y + (size_t)row * 1024 + col0);
;                     f32x4 v0 = acc[ai][bj][m][0] + b0, v1 = acc[ai][bj][m][1] + b1;
;                     v0[0] = __uint_as_float(yv.x << 16) * sigmoidf_(v0[0]); v0[1] = __uint_as_float(yv.x & 0xffff0000u) * sigmoidf_(v0[1]);
;                     v0[2] = __uint_as_float(yv.y << 16) * sigmoidf_(v0[2]); v0[3] = __uint_as_float(yv.y & 0xffff0000u) * sigmoidf_(v0[3]);
;                     v1[0] = __uint_as_float(yv.z << 16) * sigmoidf_(v1[0]); v1[1] = __uint_as_float(yv.z & 0xffff0000u) * sigmoidf_(v1[1]);
;                     v1[2] = __uint_as_float(yv.w << 16) * sigmoidf_(v1[2]); v1[3] = __uint_as_float(yv.w & 0xffff0000u) * sigmoidf_(v1[3]);
;                     *(u32x4*)(MIX + (size_t)row * 2048 + 1024 + col0) = pack8(v0, v1);
;                     float ss = (v0[0] * v0[0] + v0[1] * v0[1]) + (v0[2] * v0[2] + v0[3] * v0[3]) + (v1[0] * v1[0] + v1[1] * v1[1]) + (v1[2] * v1[2] + v1[3] * v1[3]);
;                     ss += __shfl_xor(ss, 16); ss += __shfl_xor(ss, 32);
;                     if (fq == 0) atomicAdd(rsq + row, ss); } }
;     }
	v_add_f32_e32 v16, v16, v17
	ds_bpermute_b32 v17, v135, v16
	global_store_dwordx4 v[82:83], v[18:21], off offset:2304
	s_waitcnt lgkmcnt(0)
	v_add_f32_e32 v176, v16, v17
	v_mov_b32_e32 v178, v80
	v_mov_b32_e32 v179, v81
	s_waitcnt lgkmcnt(0)
	global_load_dwordx4 v[16:19], v[84:85], off offset:256
	s_and_saveexec_b64 s[10:11], s[4:5]
	global_atomic_add_f32 v[178:179], v176, off
	s_mov_b64 exec, s[10:11]
	v_pk_add_f32 v[14:15], v[14:15], v[70:71]
	v_pk_add_f32 v[12:13], v[12:13], v[68:69]
	v_pk_add_f32 v[8:9], v[8:9], v[64:65]
	v_mul_f32_e32 v13, 0xbfb8aa3b, v13
	v_mul_f32_e32 v15, 0xbfb8aa3b, v15
	v_pk_add_f32 v[10:11], v[10:11], v[66:67]
	v_mul_f32_e32 v12, 0xbfb8aa3b, v12
	v_mul_f32_e32 v14, 0xbfb8aa3b, v14
	v_mul_f32_e32 v8, 0xbfb8aa3b, v8
	v_mul_f32_e32 v9, 0xbfb8aa3b, v9
	v_exp_f32_e32 v13, v13
	v_exp_f32_e32 v15, v15
	v_mul_f32_e32 v10, 0xbfb8aa3b, v10
	v_mul_f32_e32 v11, 0xbfb8aa3b, v11
	v_exp_f32_e32 v12, v12
	v_exp_f32_e32 v14, v14
	v_exp_f32_e32 v8, v8
	v_exp_f32_e32 v9, v9
	v_exp_f32_e32 v10, v10
	v_exp_f32_e32 v11, v11
	v_add_f32_e32 v13, 1.0, v13
	v_add_f32_e32 v15, 1.0, v15
	v_add_f32_e32 v12, 1.0, v12
	v_add_f32_e32 v14, 1.0, v14
	v_add_f32_e32 v8, 1.0, v8
	v_add_f32_e32 v9, 1.0, v9
	v_rcp_f32_e32 v13, v13
	v_rcp_f32_e32 v15, v15
	v_add_f32_e32 v10, 1.0, v10
	v_add_f32_e32 v11, 1.0, v11
	v_rcp_f32_e32 v12, v12
	v_rcp_f32_e32 v14, v14
	v_rcp_f32_e32 v8, v8
	v_rcp_f32_e32 v9, v9
	v_rcp_f32_e32 v10, v10
	v_rcp_f32_e32 v11, v11
	s_waitcnt vmcnt(1)
	v_lshlrev_b32_e32 v20, 16, v16
	v_and_b32_e32 v16, 0xffff0000, v16
	v_lshlrev_b32_e32 v21, 16, v17
	v_and_b32_e32 v17, 0xffff0000, v17
	v_lshlrev_b32_e32 v22, 16, v18
	v_and_b32_e32 v18, 0xffff0000, v18
	v_mul_f32_e32 v13, v13, v16
	v_mul_f32_e32 v15, v15, v17
	v_lshlrev_b32_e32 v23, 16, v19
	v_and_b32_e32 v19, 0xffff0000, v19
	v_mul_f32_e32 v12, v12, v20
	v_mul_f32_e32 v14, v14, v21
	v_mul_f32_e32 v16, v8, v22
	v_mul_f32_e32 v17, v9, v18
	v_mul_f32_e32 v8, v13, v13
	v_mul_f32_e32 v9, v15, v15
	v_mul_f32_e32 v18, v10, v23
	v_mul_f32_e32 v19, v11, v19
	v_mul_f32_e32 v10, v17, v17
	v_fmac_f32_e32 v8, v12, v12
	v_fmac_f32_e32 v9, v14, v14
	v_mul_f32_e32 v11, v19, v19
	v_fmac_f32_e32 v10, v16, v16
	v_add_f32_e32 v8, v8, v9
	v_add_f32_e32 v8, v10, v8
	v_fmac_f32_e32 v11, v18, v18
	v_add_f32_e32 v8, v11, v8
	ds_bpermute_b32 v9, v134, v8
	v_cvt_pk_bf16_f32 v10, v12, v13
	v_cvt_pk_bf16_f32 v11, v14, v15
	v_cvt_pk_bf16_f32 v12, v16, v17
	v_cvt_pk_bf16_f32 v13, v18, v19
	s_waitcnt lgkmcnt(0)
	v_add_f32_e32 v8, v8, v9
	ds_bpermute_b32 v9, v135, v8
	global_store_dwordx4 v[74:75], v[10:13], off offset:2304
	s_waitcnt lgkmcnt(0)
	v_add_f32_e32 v176, v8, v9
	v_mov_b32_e32 v178, v72
	v_mov_b32_e32 v179, v73
	s_waitcnt lgkmcnt(0)
	global_load_dwordx4 v[8:11], v[78:79], off offset:256
	s_and_saveexec_b64 s[10:11], s[4:5]
	global_atomic_add_f32 v[178:179], v176, off
	s_mov_b64 exec, s[10:11]
	v_pk_add_f32 v[6:7], v[6:7], v[70:71]
	v_pk_add_f32 v[4:5], v[4:5], v[68:69]
	v_pk_add_f32 v[0:1], v[0:1], v[64:65]
	v_mul_f32_e32 v5, 0xbfb8aa3b, v5
	v_mul_f32_e32 v7, 0xbfb8aa3b, v7
	v_pk_add_f32 v[2:3], v[2:3], v[66:67]
	v_mul_f32_e32 v4, 0xbfb8aa3b, v4
	v_mul_f32_e32 v6, 0xbfb8aa3b, v6
	v_mul_f32_e32 v0, 0xbfb8aa3b, v0
	v_mul_f32_e32 v1, 0xbfb8aa3b, v1
	v_exp_f32_e32 v5, v5
	v_exp_f32_e32 v7, v7
	v_mul_f32_e32 v2, 0xbfb8aa3b, v2
	v_mul_f32_e32 v3, 0xbfb8aa3b, v3
	v_exp_f32_e32 v4, v4
	v_exp_f32_e32 v6, v6
	v_exp_f32_e32 v0, v0
	v_exp_f32_e32 v1, v1
	v_exp_f32_e32 v2, v2
	v_exp_f32_e32 v3, v3
	v_add_f32_e32 v5, 1.0, v5
	v_add_f32_e32 v7, 1.0, v7
	v_add_f32_e32 v4, 1.0, v4
	v_add_f32_e32 v6, 1.0, v6
	v_add_f32_e32 v0, 1.0, v0
	v_add_f32_e32 v1, 1.0, v1
	v_rcp_f32_e32 v5, v5
	v_rcp_f32_e32 v7, v7
	v_add_f32_e32 v2, 1.0, v2
	v_add_f32_e32 v3, 1.0, v3
	v_rcp_f32_e32 v4, v4
	v_rcp_f32_e32 v6, v6
	v_rcp_f32_e32 v0, v0
	v_rcp_f32_e32 v1, v1
	v_rcp_f32_e32 v2, v2
	v_rcp_f32_e32 v3, v3
	s_waitcnt vmcnt(1)
	v_lshlrev_b32_e32 v12, 16, v8
	v_and_b32_e32 v8, 0xffff0000, v8
	v_lshlrev_b32_e32 v13, 16, v9
	v_and_b32_e32 v9, 0xffff0000, v9
	v_lshlrev_b32_e32 v14, 16, v10
	v_and_b32_e32 v10, 0xffff0000, v10
	v_mul_f32_e32 v5, v5, v8
	v_mul_f32_e32 v7, v7, v9
	v_lshlrev_b32_e32 v15, 16, v11
	v_and_b32_e32 v11, 0xffff0000, v11
	v_mul_f32_e32 v4, v4, v12
	v_mul_f32_e32 v6, v6, v13
	v_mul_f32_e32 v8, v0, v14
	v_mul_f32_e32 v9, v1, v10
	v_mul_f32_e32 v0, v5, v5
	v_mul_f32_e32 v1, v7, v7
	v_mul_f32_e32 v10, v2, v15
	v_mul_f32_e32 v11, v3, v11
	v_mul_f32_e32 v2, v9, v9
	v_fmac_f32_e32 v0, v4, v4
	v_fmac_f32_e32 v1, v6, v6
	v_mul_f32_e32 v3, v11, v11
	v_fmac_f32_e32 v2, v8, v8
	v_add_f32_e32 v0, v0, v1
	v_add_f32_e32 v0, v2, v0
	v_fmac_f32_e32 v3, v10, v10
	v_add_f32_e32 v0, v3, v0
	ds_bpermute_b32 v1, v134, v0
	v_cvt_pk_bf16_f32 v2, v4, v5
	v_cvt_pk_bf16_f32 v3, v6, v7
	v_cvt_pk_bf16_f32 v4, v8, v9
	v_cvt_pk_bf16_f32 v5, v10, v11
	s_waitcnt lgkmcnt(0)
	v_add_f32_e32 v0, v0, v1
	ds_bpermute_b32 v1, v135, v0
	global_store_dwordx4 v[86:87], v[2:5], off offset:2304
	s_and_saveexec_b64 s[10:11], s[4:5]
	s_cbranch_execz .LBB0_631
	s_waitcnt lgkmcnt(0)
	v_add_f32_e32 v0, v0, v1
	global_atomic_add_f32 v[76:77], v0, off
